# ctx units remapped so each CU runs only 2 mixer code paths (icache reuse) + D-mixer o1 park pipelined
# baseline (speedup 1.0000x reference)
.LBB0_64:
	s_cmp_lt_u32 s96, 2
	v_readlane_b32 s10, v253, 6
	s_cselect_b64 s[8:9], -1, 0
	v_readlane_b32 s11, v253, 7
	s_and_b64 s[8:9], s[10:11], s[8:9]
	s_sub_i32 s10, 1, s96
	s_and_b64 s[8:9], s[8:9], exec
	s_cselect_b32 s8, s10, s96
	s_mul_i32 s8, s8, s50
	s_add_i32 s8, s8, s2
	s_cmpk_lt_i32 s8, 0x200
	s_mov_b64 s[6:7], -1
	v_mov_b32_e32 v145, v164
	s_cselect_b64 s[40:41], -1, 0
	s_cmpk_gt_i32 s8, 0x1ff
	s_cbranch_scc0 .LBB0_66
	s_cmpk_lg_i32 s50, 0x100
	s_cbranch_scc1 .Lctx_map_orig
	s_bfe_u32 s6, s2, 0x20005
	s_sub_i32 s7, 3, s6
	s_lshr_b32 s97, s2, 7
	s_cmp_eq_u32 s96, 2
	s_cselect_b32 s6, s6, s7
	s_cselect_b32 s7, 0, 2
	s_add_i32 s97, s97, s7
	s_lshl_b32 s6, s6, 2
	s_add_i32 s97, s97, s6
	s_lshl_b32 s6, s2, 8
	s_and_b32 s19, s6, 0x1f00
	s_mov_b64 s[6:7], 0
	s_branch .LBB0_66
.Lctx_map_orig:
	s_add_i32 s6, s8, 0xfffffe00
	s_lshr_b32 s97, s6, 5
	s_lshl_b32 s6, s8, 8
	s_and_b32 s19, s6, 0x1f00
	s_mov_b64 s[6:7], 0

.LBB0_110:
	v_add_f32_e32 v2, 0, v2
	v_add_f32_e32 v2, v88, v2
	v_add_f32_e32 v2, v89, v2
	v_add_f32_e32 v3, 0, v92
	v_add_f32_e32 v2, v90, v2
	v_add_f32_e32 v3, v93, v3
	v_add_f32_e32 v2, v91, v2
	v_add_f32_e32 v3, v94, v3
	v_add_f32_e32 v2, v108, v2
	v_add_f32_e32 v3, v95, v3
	v_add_f32_e32 v2, v109, v2
	v_add_f32_e32 v3, v96, v3
	v_add_f32_e32 v2, v110, v2
	v_add_f32_e32 v3, v97, v3
	v_add_f32_e32 v2, v84, v2
	v_add_f32_e32 v3, v98, v3
	v_add_f32_e32 v2, v85, v2
	v_add_f32_e32 v3, v99, v3
	v_add_f32_e32 v2, v86, v2
	v_add_f32_e32 v3, v100, v3
	v_add_f32_e32 v2, v87, v2
	v_add_f32_e32 v3, v101, v3
	v_add_f32_e32 v2, v111, v2
	v_add_f32_e32 v3, v102, v3
	v_add_f32_e32 v2, v112, v2
	v_add_f32_e32 v3, v103, v3
	v_add_f32_e32 v2, v113, v2
	v_add_f32_e32 v3, v104, v3
	v_add_f32_e32 v2, v114, v2
	v_add_f32_e32 v3, v105, v3
	v_add_f32_e32 v116, v2, v138
	v_add_u32_e32 v2, s7, v150
	v_add_f32_e32 v3, v106, v3
	v_add_u32_e32 v159, v2, v152
	v_add_f32_e32 v3, v107, v3
	ds_read_b64_tr_b16 v[86:87], v159 offset:31232
	ds_read_b64_tr_b16 v[84:85], v159 offset:26624
	ds_read_b64_tr_b16 v[88:89], v159 offset:26656
	ds_read_b64_tr_b16 v[90:91], v159 offset:31264
	ds_read_b64_tr_b16 v[92:93], v159 offset:26688
	ds_read_b64_tr_b16 v[94:95], v159 offset:31296
	ds_read_b64_tr_b16 v[96:97], v159 offset:26720
	ds_read_b64_tr_b16 v[98:99], v159 offset:31328
	ds_read_b64_tr_b16 v[100:101], v159 offset:26752
	ds_read_b64_tr_b16 v[102:103], v159 offset:31360
	ds_read_b64_tr_b16 v[104:105], v159 offset:26784
	ds_read_b64_tr_b16 v[106:107], v159 offset:31392
	ds_read_b64_tr_b16 v[108:109], v159 offset:26816
	ds_read_b64_tr_b16 v[110:111], v159 offset:31424
	ds_read_b64_tr_b16 v[112:113], v159 offset:26848
	ds_read_b64_tr_b16 v[114:115], v159 offset:31456
	s_mov_b32 s6, 0
	v_add_f32_e32 v0, v3, v0
	s_waitcnt lgkmcnt(14)
	v_mfma_f32_16x16x32_bf16 v[64:67], v[84:87], v[72:75], v[64:67]
	v_mfma_f32_16x16x32_bf16 v[60:63], v[84:87], v[80:83], v[60:63]
	s_waitcnt lgkmcnt(12)
	v_mfma_f32_16x16x32_bf16 v[56:59], v[88:91], v[72:75], v[56:59]
	v_mfma_f32_16x16x32_bf16 v[52:55], v[88:91], v[80:83], v[52:55]
	s_waitcnt lgkmcnt(10)
	v_mfma_f32_16x16x32_bf16 v[48:51], v[92:95], v[72:75], v[48:51]
	v_mfma_f32_16x16x32_bf16 v[44:47], v[92:95], v[80:83], v[44:47]
	s_waitcnt lgkmcnt(8)
	v_mfma_f32_16x16x32_bf16 v[40:43], v[96:99], v[72:75], v[40:43]
	v_mfma_f32_16x16x32_bf16 v[36:39], v[96:99], v[80:83], v[36:39]
	ds_read_b64_tr_b16 v[84:85], v159 offset:35840
	ds_read_b64_tr_b16 v[88:89], v159 offset:35872
	ds_read_b64_tr_b16 v[92:93], v159 offset:35904
	ds_read_b64_tr_b16 v[96:97], v159 offset:35936
	ds_read_b64_tr_b16 v[86:87], v159 offset:40448
	ds_read_b64_tr_b16 v[90:91], v159 offset:40480
	ds_read_b64_tr_b16 v[94:95], v159 offset:40512
	ds_read_b64_tr_b16 v[98:99], v159 offset:40544
	s_waitcnt lgkmcnt(14)
	v_mfma_f32_16x16x32_bf16 v[32:35], v[100:103], v[72:75], v[32:35]
	v_mfma_f32_16x16x32_bf16 v[28:31], v[100:103], v[80:83], v[28:31]
	s_waitcnt lgkmcnt(12)
	v_mfma_f32_16x16x32_bf16 v[24:27], v[104:107], v[72:75], v[24:27]
	v_mfma_f32_16x16x32_bf16 v[20:23], v[104:107], v[80:83], v[20:23]
	s_waitcnt lgkmcnt(10)
	v_mfma_f32_16x16x32_bf16 v[100:103], v[108:111], v[72:75], v[16:19]
	s_waitcnt lgkmcnt(8)
	v_mfma_f32_16x16x32_bf16 v[72:75], v[112:115], v[72:75], v[8:11]
	v_mfma_f32_16x16x32_bf16 v[2:5], v[112:115], v[80:83], v[4:7]
	v_mfma_f32_16x16x32_bf16 v[104:107], v[108:111], v[80:83], v[12:15]
	s_nop 1
	ds_read_b64_tr_b16 v[6:7], v159 offset:35968
	ds_read_b64_tr_b16 v[10:11], v159 offset:36000
	ds_read_b64_tr_b16 v[80:81], v159 offset:36032
	ds_read_b64_tr_b16 v[108:109], v159 offset:36064
	ds_read_b64_tr_b16 v[8:9], v159 offset:40576
	ds_read_b64_tr_b16 v[12:13], v159 offset:40608
	ds_read_b64_tr_b16 v[82:83], v159 offset:40640
	ds_read_b64_tr_b16 v[110:111], v159 offset:40672
	s_waitcnt lgkmcnt(11)
	v_mfma_f32_16x16x32_bf16 v[64:67], v[84:87], v[68:71], v[64:67]
	v_mfma_f32_16x16x32_bf16 v[60:63], v[84:87], v[76:79], v[60:63]
	s_waitcnt lgkmcnt(10)
	v_mfma_f32_16x16x32_bf16 v[56:59], v[88:91], v[68:71], v[56:59]
	v_mfma_f32_16x16x32_bf16 v[52:55], v[88:91], v[76:79], v[52:55]
	s_waitcnt lgkmcnt(9)
	v_mfma_f32_16x16x32_bf16 v[48:51], v[92:95], v[68:71], v[48:51]
	v_mfma_f32_16x16x32_bf16 v[44:47], v[92:95], v[76:79], v[44:47]
	s_waitcnt lgkmcnt(8)
	v_mfma_f32_16x16x32_bf16 v[40:43], v[96:99], v[68:71], v[40:43]
	v_mfma_f32_16x16x32_bf16 v[14:17], v[96:99], v[76:79], v[36:39]
	s_waitcnt lgkmcnt(3)
	v_mfma_f32_16x16x32_bf16 v[32:35], v[6:9], v[68:71], v[32:35]
	v_mfma_f32_16x16x32_bf16 v[28:31], v[6:9], v[76:79], v[28:31]
	s_waitcnt lgkmcnt(2)
	v_mfma_f32_16x16x32_bf16 v[24:27], v[10:13], v[68:71], v[24:27]
	v_mfma_f32_16x16x32_bf16 v[10:13], v[10:13], v[76:79], v[20:23]
	s_waitcnt lgkmcnt(1)
	v_mfma_f32_16x16x32_bf16 v[18:21], v[80:83], v[68:71], v[100:103]
	v_mfma_f32_16x16x32_bf16 v[6:9], v[80:83], v[76:79], v[104:107]
	s_waitcnt lgkmcnt(0)
	v_mfma_f32_16x16x32_bf16 v[36:39], v[108:111], v[68:71], v[72:75]
	v_mfma_f32_16x16x32_bf16 v[2:5], v[108:111], v[76:79], v[2:5]
	v_and_b32_e32 v23, 64, v226
	v_xor_b32_e32 v22, 16, v226
	v_add_u32_e32 v158, 64, v23
	v_cmp_lt_i32_e32 vcc, v22, v158
	s_barrier
	s_nop 0
	v_cndmask_b32_e32 v22, v226, v22, vcc
	v_lshlrev_b32_e32 v156, 2, v22
	ds_bpermute_b32 v23, v156, v0
	v_xor_b32_e32 v22, 32, v226
	v_cmp_lt_i32_e32 vcc, v22, v158
	s_waitcnt lgkmcnt(0)
	s_mov_b32 s7, 0x10000
	v_cndmask_b32_e32 v22, v226, v22, vcc
	v_lshlrev_b32_e32 v157, 2, v22
	v_add_f32_e32 v0, v0, v23
	ds_bpermute_b32 v22, v156, v116
	ds_bpermute_b32 v23, v157, v0
	v_lshl_add_u64 v[142:143], s[66:67], 0, v[142:143]
	v_mov_b32_e32 v174, 0xf149f2ca
	v_mov_b32_e32 v173, 0
	s_waitcnt lgkmcnt(1)
	v_add_f32_e32 v22, v116, v22
	s_waitcnt lgkmcnt(0)
	v_add_f32_e32 v69, v0, v23
	ds_bpermute_b32 v68, v157, v22
	v_div_scale_f32 v70, s[62:63], v69, v69, 1.0
	v_rcp_f32_e32 v71, v70
	v_lshlrev_b32_e32 v0, 1, v148
	s_waitcnt lgkmcnt(0)
	v_add_f32_e32 v72, v22, v68
	v_lshl_add_u64 v[22:23], s[84:85], 0, v[0:1]
	v_fma_f32 v0, -v70, v71, 1.0
	v_fmac_f32_e32 v71, v0, v71
	v_div_scale_f32 v0, vcc, 1.0, v69, 1.0
	v_mul_f32_e32 v68, v0, v71
	v_fma_f32 v73, -v70, v68, v0
	v_fmac_f32_e32 v68, v73, v71
	v_fma_f32 v0, -v70, v68, v0
	v_div_fmas_f32 v0, v0, v71, v68
	v_div_fixup_f32 v68, v0, v69, 1.0
	v_lshlrev_b32_e32 v0, 12, v167
	v_lshl_add_u64 v[136:137], v[22:23], 0, v[0:1]
	v_pk_mul_f32 v[22:23], v[66:67], v[68:69] op_sel_hi:[1,0]
	v_pk_mul_f32 v[64:65], v[64:65], v[68:69] op_sel_hi:[1,0]
	v_pk_mul_f32 v[56:57], v[56:57], v[68:69] op_sel_hi:[1,0]
	v_cvt_pk_bf16_f32 v64, v64, v65
	v_cvt_pk_bf16_f32 v65, v22, v23
	v_pk_mul_f32 v[22:23], v[58:59], v[68:69] op_sel_hi:[1,0]
	global_store_dwordx2 v[136:137], v[64:65], off
	s_nop 1
	v_cvt_pk_bf16_f32 v56, v56, v57
	v_cvt_pk_bf16_f32 v57, v22, v23
	v_pk_mul_f32 v[22:23], v[50:51], v[68:69] op_sel_hi:[1,0]
	v_pk_mul_f32 v[48:49], v[48:49], v[68:69] op_sel_hi:[1,0]
	global_store_dwordx2 v[136:137], v[56:57], off offset:32
	s_nop 1
	v_cvt_pk_bf16_f32 v48, v48, v49
	v_cvt_pk_bf16_f32 v49, v22, v23
	v_pk_mul_f32 v[22:23], v[42:43], v[68:69] op_sel_hi:[1,0]
	v_pk_mul_f32 v[40:41], v[40:41], v[68:69] op_sel_hi:[1,0]
	global_store_dwordx2 v[136:137], v[48:49], off offset:64
	s_nop 1
	v_cvt_pk_bf16_f32 v40, v40, v41
	v_cvt_pk_bf16_f32 v41, v22, v23
	v_pk_mul_f32 v[22:23], v[34:35], v[68:69] op_sel_hi:[1,0]
	v_pk_mul_f32 v[32:33], v[32:33], v[68:69] op_sel_hi:[1,0]
	global_store_dwordx2 v[136:137], v[40:41], off offset:96
	s_nop 1
	v_cvt_pk_bf16_f32 v32, v32, v33
	v_cvt_pk_bf16_f32 v33, v22, v23
	v_pk_mul_f32 v[22:23], v[26:27], v[68:69] op_sel_hi:[1,0]
	v_pk_mul_f32 v[24:25], v[24:25], v[68:69] op_sel_hi:[1,0]
	v_div_scale_f32 v0, s[62:63], v72, v72, 1.0
	global_store_dwordx2 v[136:137], v[32:33], off offset:128
	s_nop 1
	v_cvt_pk_bf16_f32 v24, v24, v25
	v_cvt_pk_bf16_f32 v25, v22, v23
	v_rcp_f32_e32 v22, v0
	v_pk_mul_f32 v[18:19], v[18:19], v[68:69] op_sel_hi:[1,0]
	global_store_dwordx2 v[136:137], v[24:25], off offset:160
	s_nop 1
	v_pk_mul_f32 v[20:21], v[20:21], v[68:69] op_sel_hi:[1,0]
	v_cvt_pk_bf16_f32 v18, v18, v19
	s_mov_b64 s[62:63], 0x10000
	v_cvt_pk_bf16_f32 v19, v20, v21
	global_store_dwordx2 v[136:137], v[18:19], off offset:192
	s_nop 1
	v_pk_mul_f32 v[18:19], v[38:39], v[68:69] op_sel_hi:[1,0]
	v_pk_mul_f32 v[20:21], v[36:37], v[68:69] op_sel_hi:[1,0]
	v_lshl_add_u64 v[140:141], v[136:137], 0, s[62:63]
	v_cvt_pk_bf16_f32 v20, v20, v21
	v_cvt_pk_bf16_f32 v21, v18, v19
	v_fma_f32 v18, -v0, v22, 1.0
	v_fmac_f32_e32 v22, v18, v22
	v_div_scale_f32 v18, vcc, 1.0, v72, 1.0
	v_mul_f32_e32 v19, v18, v22
	global_store_dwordx2 v[136:137], v[20:21], off offset:224
	s_nop 1
	v_fma_f32 v20, -v0, v19, v18
	v_fmac_f32_e32 v19, v20, v22
	v_fma_f32 v0, -v0, v19, v18
	v_div_fmas_f32 v0, v0, v22, v19
	v_div_fixup_f32 v0, v0, v72, 1.0
	v_pk_mul_f32 v[18:19], v[62:63], v[0:1] op_sel_hi:[1,0]
	v_pk_mul_f32 v[20:21], v[60:61], v[0:1] op_sel_hi:[1,0]
	v_pk_mul_f32 v[22:23], v[52:53], v[0:1] op_sel_hi:[1,0]
	v_cvt_pk_bf16_f32 v20, v20, v21
	v_cvt_pk_bf16_f32 v21, v18, v19
	v_add_co_u32_e32 v18, vcc, s7, v136
	v_pk_mul_f32 v[16:17], v[16:17], v[0:1] op_sel_hi:[1,0]
	s_nop 0
	v_addc_co_u32_e32 v19, vcc, 0, v137, vcc
	global_store_dwordx2 v[18:19], v[20:21], off
	s_nop 1
	v_pk_mul_f32 v[20:21], v[54:55], v[0:1] op_sel_hi:[1,0]
	v_cvt_pk_bf16_f32 v22, v22, v23
	v_pk_mul_f32 v[14:15], v[14:15], v[0:1] op_sel_hi:[1,0]
	v_cvt_pk_bf16_f32 v23, v20, v21
	global_store_dwordx2 v[18:19], v[22:23], off offset:32
	s_nop 1
	v_pk_mul_f32 v[22:23], v[44:45], v[0:1] op_sel_hi:[1,0]
	v_pk_mul_f32 v[20:21], v[46:47], v[0:1] op_sel_hi:[1,0]
	v_cvt_pk_bf16_f32 v22, v22, v23
	v_pk_mul_f32 v[10:11], v[10:11], v[0:1] op_sel_hi:[1,0]
	v_cvt_pk_bf16_f32 v23, v20, v21
	global_store_dwordx2 v[18:19], v[22:23], off offset:64
	s_nop 1
	v_cvt_pk_bf16_f32 v14, v14, v15
	v_cvt_pk_bf16_f32 v15, v16, v17
	v_pk_mul_f32 v[16:17], v[28:29], v[0:1] op_sel_hi:[1,0]
	v_pk_mul_f32 v[6:7], v[6:7], v[0:1] op_sel_hi:[1,0]
	v_pk_mul_f32 v[2:3], v[2:3], v[0:1] op_sel_hi:[1,0]
	global_store_dwordx2 v[18:19], v[14:15], off offset:96
	s_nop 1
	v_pk_mul_f32 v[14:15], v[30:31], v[0:1] op_sel_hi:[1,0]
	v_cvt_pk_bf16_f32 v16, v16, v17
	v_pk_mul_f32 v[12:13], v[12:13], v[0:1] op_sel_hi:[1,0]
	v_cvt_pk_bf16_f32 v17, v14, v15
	global_store_dwordx2 v[18:19], v[16:17], off offset:128
	s_nop 1
	v_cvt_pk_bf16_f32 v10, v10, v11
	v_cvt_pk_bf16_f32 v11, v12, v13
	global_store_dwordx2 v[18:19], v[10:11], off offset:160
	s_nop 1
	v_pk_mul_f32 v[8:9], v[8:9], v[0:1] op_sel_hi:[1,0]
	v_cvt_pk_bf16_f32 v6, v6, v7
	v_pk_mul_f32 v[4:5], v[4:5], v[0:1] op_sel_hi:[1,0]
	v_cvt_pk_bf16_f32 v7, v8, v9
	global_store_dwordx2 v[18:19], v[6:7], off offset:192
	s_nop 1
	v_cvt_pk_bf16_f32 v2, v2, v3
	v_cvt_pk_bf16_f32 v3, v4, v5
	global_store_dwordx2 v[18:19], v[2:3], off offset:224
	s_nop 1
	global_load_dwordx4 v[76:79], v[124:125], off offset:128
	global_load_dwordx4 v[68:71], v[124:125], off offset:192
	global_load_dwordx4 v[80:83], v[126:127], off offset:128
	global_load_dwordx4 v[72:75], v[126:127], off offset:192
	global_load_dwordx4 v[84:87], v[128:129], off offset:128
	global_load_dwordx4 v[92:95], v[130:131], off
	global_load_dwordx4 v[88:91], v[132:133], off
	s_mov_b64 s[62:63], 0x10020
	v_lshl_add_u64 v[138:139], v[136:137], 0, s[62:63]
	s_mov_b64 s[62:63], 0x10040
	v_lshl_add_u64 v[134:135], v[136:137], 0, s[62:63]
	s_mov_b64 s[62:63], 0x10060
	v_lshl_add_u64 v[132:133], v[136:137], 0, s[62:63]
	s_mov_b64 s[62:63], 0x10080
	v_lshl_add_u64 v[130:131], v[136:137], 0, s[62:63]
	s_mov_b64 s[62:63], 0x100a0
	v_lshl_add_u64 v[128:129], v[136:137], 0, s[62:63]
	s_mov_b64 s[62:63], 0x100c0
	v_mov_b32_e32 v2, v1
	v_mov_b32_e32 v3, v1
	v_lshl_add_u64 v[126:127], v[136:137], 0, s[62:63]
	s_mov_b64 s[62:63], 0x100e0
	v_mov_b32_e32 v0, v1
	v_mov_b64_e32 v[6:7], v[2:3]
	v_mov_b64_e32 v[10:11], v[2:3]
	v_mov_b64_e32 v[14:15], v[2:3]
	v_mov_b64_e32 v[18:19], v[2:3]
	v_mov_b64_e32 v[22:23], v[2:3]
	v_mov_b64_e32 v[26:27], v[2:3]
	v_mov_b64_e32 v[30:31], v[2:3]
	v_mov_b64_e32 v[34:35], v[2:3]
	v_mov_b64_e32 v[38:39], v[2:3]
	v_mov_b64_e32 v[42:43], v[2:3]
	v_mov_b64_e32 v[46:47], v[2:3]
	v_mov_b64_e32 v[50:51], v[2:3]
	v_mov_b64_e32 v[54:55], v[2:3]
	v_mov_b64_e32 v[58:59], v[2:3]
	v_mov_b64_e32 v[62:63], v[2:3]
	v_mov_b64_e32 v[66:67], v[2:3]
	v_lshl_add_u64 v[124:125], v[136:137], 0, s[62:63]
	v_mov_b64_e32 v[4:5], v[0:1]
	v_mov_b64_e32 v[8:9], v[0:1]
	v_mov_b64_e32 v[12:13], v[0:1]
	v_mov_b64_e32 v[16:17], v[0:1]
	v_mov_b64_e32 v[20:21], v[0:1]
	v_mov_b64_e32 v[24:25], v[0:1]
	v_mov_b64_e32 v[28:29], v[0:1]
	v_mov_b64_e32 v[32:33], v[0:1]
	v_mov_b64_e32 v[36:37], v[0:1]
	v_mov_b64_e32 v[40:41], v[0:1]
	v_mov_b64_e32 v[44:45], v[0:1]
	v_mov_b64_e32 v[48:49], v[0:1]
	v_mov_b64_e32 v[52:53], v[0:1]
	v_mov_b64_e32 v[56:57], v[0:1]
	v_mov_b64_e32 v[60:61], v[0:1]
	v_mov_b64_e32 v[64:65], v[0:1]
	v_mov_b32_e32 v0, 0
	v_mov_b32_e32 v3, 0xf149f2ca

.LBB0_121:
	v_add_f32_e32 v3, 0, v92
	v_add_f32_e32 v2, 0, v2
	v_add_f32_e32 v3, v93, v3
	v_add_f32_e32 v2, v88, v2
	v_add_f32_e32 v3, v94, v3
	v_add_f32_e32 v2, v89, v2
	v_add_f32_e32 v3, v95, v3
	v_add_f32_e32 v2, v90, v2
	v_add_f32_e32 v3, v96, v3
	v_add_f32_e32 v2, v91, v2
	v_add_f32_e32 v3, v97, v3
	v_add_f32_e32 v2, v108, v2
	v_add_f32_e32 v3, v98, v3
	v_add_f32_e32 v2, v109, v2
	v_add_f32_e32 v3, v99, v3
	v_add_f32_e32 v2, v110, v2
	v_add_f32_e32 v3, v100, v3
	v_add_f32_e32 v2, v84, v2
	v_add_f32_e32 v3, v101, v3
	v_add_f32_e32 v2, v85, v2
	v_add_f32_e32 v3, v102, v3
	v_add_f32_e32 v2, v86, v2
	v_add_f32_e32 v3, v103, v3
	v_add_f32_e32 v2, v87, v2
	v_add_f32_e32 v3, v104, v3
	v_add_f32_e32 v2, v111, v2
	v_add_f32_e32 v3, v105, v3
	v_add_f32_e32 v2, v112, v2
	v_add_f32_e32 v3, v106, v3
	v_add_f32_e32 v2, v113, v2
	v_add_f32_e32 v3, v107, v3
	v_add_f32_e32 v2, v114, v2
	ds_read_b64_tr_b16 v[86:87], v159 offset:31232
	ds_read_b64_tr_b16 v[84:85], v159 offset:26624
	ds_read_b64_tr_b16 v[88:89], v159 offset:26656
	ds_read_b64_tr_b16 v[90:91], v159 offset:31264
	ds_read_b64_tr_b16 v[92:93], v159 offset:26688
	ds_read_b64_tr_b16 v[94:95], v159 offset:31296
	ds_read_b64_tr_b16 v[96:97], v159 offset:26720
	ds_read_b64_tr_b16 v[98:99], v159 offset:31328
	ds_read_b64_tr_b16 v[100:101], v159 offset:26752
	ds_read_b64_tr_b16 v[102:103], v159 offset:31360
	ds_read_b64_tr_b16 v[104:105], v159 offset:26784
	ds_read_b64_tr_b16 v[106:107], v159 offset:31392
	ds_read_b64_tr_b16 v[108:109], v159 offset:26816
	ds_read_b64_tr_b16 v[110:111], v159 offset:31424
	ds_read_b64_tr_b16 v[112:113], v159 offset:26848
	ds_read_b64_tr_b16 v[114:115], v159 offset:31456
	v_add_f32_e32 v0, v3, v0
	v_add_f32_e32 v142, v2, v173
	s_waitcnt lgkmcnt(14)
	v_mfma_f32_16x16x32_bf16 v[64:67], v[84:87], v[72:75], v[64:67]
	s_waitcnt lgkmcnt(12)
	v_mfma_f32_16x16x32_bf16 v[56:59], v[88:91], v[72:75], v[56:59]
	v_mfma_f32_16x16x32_bf16 v[52:55], v[88:91], v[80:83], v[52:55]
	s_waitcnt lgkmcnt(8)
	v_mfma_f32_16x16x32_bf16 v[40:43], v[96:99], v[72:75], v[40:43]
	v_mfma_f32_16x16x32_bf16 v[84:87], v[84:87], v[80:83], v[60:63]
	v_mfma_f32_16x16x32_bf16 v[48:51], v[92:95], v[72:75], v[48:51]
	v_mfma_f32_16x16x32_bf16 v[44:47], v[92:95], v[80:83], v[44:47]
	v_mfma_f32_16x16x32_bf16 v[88:91], v[96:99], v[80:83], v[36:39]
	s_nop 2
	ds_read_b64_tr_b16 v[36:37], v159 offset:35840
	ds_read_b64_tr_b16 v[92:93], v159 offset:35872
	ds_read_b64_tr_b16 v[96:97], v159 offset:35904
	ds_read_b64_tr_b16 v[116:117], v159 offset:35936
	ds_read_b64_tr_b16 v[38:39], v159 offset:40448
	ds_read_b64_tr_b16 v[94:95], v159 offset:40480
	ds_read_b64_tr_b16 v[98:99], v159 offset:40512
	ds_read_b64_tr_b16 v[118:119], v159 offset:40544
	s_waitcnt lgkmcnt(14)
	v_mfma_f32_16x16x32_bf16 v[120:123], v[100:103], v[72:75], v[32:35]
	s_waitcnt lgkmcnt(12)
	v_mfma_f32_16x16x32_bf16 v[152:155], v[104:107], v[72:75], v[24:27]
	s_waitcnt lgkmcnt(10)
	v_mfma_f32_16x16x32_bf16 v[168:171], v[108:111], v[72:75], v[16:19]
	s_waitcnt lgkmcnt(8)
	v_mfma_f32_16x16x32_bf16 v[72:75], v[112:115], v[72:75], v[8:11]
	v_mfma_f32_16x16x32_bf16 v[2:5], v[112:115], v[80:83], v[4:7]
	v_mfma_f32_16x16x32_bf16 v[100:103], v[100:103], v[80:83], v[28:31]
	v_mfma_f32_16x16x32_bf16 v[104:107], v[104:107], v[80:83], v[20:23]
	v_mfma_f32_16x16x32_bf16 v[108:111], v[108:111], v[80:83], v[12:15]
	ds_read_b64_tr_b16 v[6:7], v159 offset:35968
	ds_read_b64_tr_b16 v[10:11], v159 offset:36000
	ds_read_b64_tr_b16 v[80:81], v159 offset:36032
	ds_read_b64_tr_b16 v[112:113], v159 offset:36064
	ds_read_b64_tr_b16 v[8:9], v159 offset:40576
	ds_read_b64_tr_b16 v[12:13], v159 offset:40608
	ds_read_b64_tr_b16 v[82:83], v159 offset:40640
	ds_read_b64_tr_b16 v[114:115], v159 offset:40672
	s_waitcnt lgkmcnt(11)
	v_mfma_f32_16x16x32_bf16 v[60:63], v[36:39], v[68:71], v[64:67]
	v_mfma_f32_16x16x32_bf16 v[30:33], v[36:39], v[76:79], v[84:87]
	s_waitcnt lgkmcnt(10)
	v_mfma_f32_16x16x32_bf16 v[64:67], v[92:95], v[68:71], v[56:59]
	v_mfma_f32_16x16x32_bf16 v[26:29], v[92:95], v[76:79], v[52:55]
	s_waitcnt lgkmcnt(9)
	v_mfma_f32_16x16x32_bf16 v[18:21], v[96:99], v[76:79], v[44:47]
	s_waitcnt lgkmcnt(8)
	v_mfma_f32_16x16x32_bf16 v[34:37], v[116:119], v[68:71], v[40:43]
	v_mfma_f32_16x16x32_bf16 v[14:17], v[116:119], v[76:79], v[88:91]
	v_mfma_f32_16x16x32_bf16 v[48:51], v[96:99], v[68:71], v[48:51]
	s_waitcnt lgkmcnt(3)
	v_mfma_f32_16x16x32_bf16 v[44:47], v[6:9], v[68:71], v[120:123]
	v_mfma_f32_16x16x32_bf16 v[22:25], v[6:9], v[76:79], v[100:103]
	s_waitcnt lgkmcnt(2)
	v_mfma_f32_16x16x32_bf16 v[56:59], v[10:13], v[68:71], v[152:155]
	v_mfma_f32_16x16x32_bf16 v[10:13], v[10:13], v[76:79], v[104:107]
	s_waitcnt lgkmcnt(1)
	v_mfma_f32_16x16x32_bf16 v[52:55], v[80:83], v[68:71], v[168:171]
	v_mfma_f32_16x16x32_bf16 v[6:9], v[80:83], v[76:79], v[108:111]
	s_waitcnt lgkmcnt(0)
	v_mfma_f32_16x16x32_bf16 v[40:43], v[112:115], v[68:71], v[72:75]
	v_mfma_f32_16x16x32_bf16 v[2:5], v[112:115], v[76:79], v[2:5]
	v_lshlrev_b32_e32 v38, 2, v149
	s_barrier
	global_load_dword v74, v38, s[52:53]
	global_load_dword v75, v38, s[52:53] offset:256
	global_load_dword v76, v38, s[52:53] offset:512
	global_load_dword v77, v38, s[52:53] offset:768
	s_nop 0
	global_load_dwordx2 v[170:171], v[136:137], off sc1
	global_load_dwordx2 v[172:173], v[136:137], off offset:32 sc1
	global_load_dwordx2 v[174:175], v[136:137], off offset:64 sc1
	global_load_dwordx2 v[176:177], v[136:137], off offset:96 sc1
	global_load_dwordx2 v[178:179], v[136:137], off offset:128 sc1
	global_load_dwordx2 v[180:181], v[136:137], off offset:160 sc1
	global_load_dwordx2 v[182:183], v[136:137], off offset:192 sc1
	global_load_dwordx2 v[184:185], v[136:137], off offset:224 sc1
	global_load_dwordx2 v[186:187], v[140:141], off sc1
	global_load_dwordx2 v[188:189], v[138:139], off sc1
	global_load_dwordx2 v[190:191], v[134:135], off sc1
	global_load_dwordx2 v[192:193], v[132:133], off sc1
	global_load_dwordx2 v[194:195], v[130:131], off sc1
	global_load_dwordx2 v[196:197], v[128:129], off sc1
	global_load_dwordx2 v[198:199], v[126:127], off sc1
	global_load_dwordx2 v[200:201], v[124:125], off sc1
	s_waitcnt vmcnt(15)
	v_mov_b32_e32 v38, v170
	v_mov_b32_e32 v39, v171
	s_waitcnt vmcnt(14)
	v_mov_b32_e32 v68, v172
	v_mov_b32_e32 v69, v173
	s_waitcnt vmcnt(13)
	v_mov_b32_e32 v70, v174
	v_mov_b32_e32 v71, v175
	v_xor_b32_e32 v72, 1, v226
	v_xor_b32_e32 v73, 2, v226
	v_cmp_lt_i32_e32 vcc, v72, v158
	v_xor_b32_e32 v78, 4, v226
	v_xor_b32_e32 v79, 8, v226
	v_cndmask_b32_e32 v82, v226, v72, vcc
	v_cmp_lt_i32_e32 vcc, v73, v158
	ds_bpermute_b32 v80, v156, v0
	ds_bpermute_b32 v81, v156, v142
	v_cndmask_b32_e32 v83, v226, v73, vcc
	s_waitcnt vmcnt(12)
	v_mov_b32_e32 v72, v176
	v_mov_b32_e32 v73, v177
	v_cmp_lt_i32_e32 vcc, v78, v158
	s_waitcnt lgkmcnt(0)
	v_add_f32_e32 v0, v0, v80
	ds_bpermute_b32 v80, v157, v0
	v_cndmask_b32_e32 v84, v226, v78, vcc
	v_cmp_lt_i32_e32 vcc, v79, v158
	v_add_f32_e32 v81, v142, v81
	ds_bpermute_b32 v86, v157, v81
	v_cndmask_b32_e32 v85, v226, v79, vcc
	s_waitcnt vmcnt(11)
	v_mov_b32_e32 v78, v178
	v_mov_b32_e32 v79, v179
	s_waitcnt vmcnt(10)
	v_mov_b32_e32 v100, v180
	v_mov_b32_e32 v101, v181
	s_waitcnt vmcnt(9)
	v_mov_b32_e32 v102, v182
	v_mov_b32_e32 v103, v183
	s_waitcnt vmcnt(8) lgkmcnt(0)
	v_mov_b32_e32 v106, v184
	v_mov_b32_e32 v107, v185
	v_add_f32_e32 v0, v0, v80
	v_div_scale_f32 v80, s[6:7], v0, v0, 1.0
	v_rcp_f32_e32 v87, v80
	v_add_f32_e32 v118, v81, v86
	v_div_scale_f32 v81, vcc, 1.0, v0, 1.0
	v_fma_f32 v86, -v80, v87, 1.0
	v_fmac_f32_e32 v87, v86, v87
	v_mul_f32_e32 v86, v81, v87
	v_fma_f32 v88, -v80, v86, v81
	v_fmac_f32_e32 v86, v88, v87
	v_lshlrev_b32_e32 v82, 2, v82
	v_fma_f32 v80, -v80, v86, v81
	v_lshlrev_b32_e32 v83, 2, v83
	v_div_fmas_f32 v80, v80, v87, v86
	v_div_fixup_f32 v108, v80, v0, 1.0
	v_lshlrev_b32_e32 v109, 2, v148
	v_lshlrev_b32_e32 v84, 2, v84
	v_lshlrev_b32_e32 v85, 2, v85
	v_pk_mul_f32 v[60:61], v[60:61], v[108:109] op_sel_hi:[1,0]
	v_pk_mul_f32 v[62:63], v[62:63], v[108:109] op_sel_hi:[1,0]
	v_pk_mul_f32 v[48:49], v[48:49], v[108:109] op_sel_hi:[1,0]
	v_pk_mul_f32 v[50:51], v[50:51], v[108:109] op_sel_hi:[1,0]
	v_pk_mul_f32 v[34:35], v[34:35], v[108:109] op_sel_hi:[1,0]
	v_pk_mul_f32 v[36:37], v[36:37], v[108:109] op_sel_hi:[1,0]
	v_mul_f32_e32 v81, v74, v75
	ds_bpermute_b32 v81, v82, v81
	v_mul_f32_e32 v88, v76, v77
	ds_bpermute_b32 v82, v82, v88
	s_waitcnt lgkmcnt(1)
	v_fmac_f32_e32 v81, v74, v75
	ds_bpermute_b32 v0, v83, v81
	s_waitcnt lgkmcnt(1)
	v_fmac_f32_e32 v82, v76, v77
	ds_bpermute_b32 v80, v83, v82
	v_pk_mul_f32 v[74:75], v[64:65], v[108:109] op_sel_hi:[1,0]
	v_pk_mul_f32 v[76:77], v[66:67], v[108:109] op_sel_hi:[1,0]
	s_waitcnt lgkmcnt(1)
	v_add_f32_e32 v0, v81, v0
	ds_bpermute_b32 v65, v84, v0
	s_waitcnt lgkmcnt(1)
	v_add_f32_e32 v64, v82, v80
	ds_bpermute_b32 v67, v84, v64
	v_lshlrev_b32_e32 v66, 16, v38
	v_and_b32_e32 v81, 0xffff0000, v68
	s_waitcnt lgkmcnt(1)
	v_add_f32_e32 v0, v0, v65
	ds_bpermute_b32 v65, v85, v0
	s_waitcnt lgkmcnt(1)
	v_add_f32_e32 v64, v64, v67
	ds_bpermute_b32 v80, v85, v64
	v_and_b32_e32 v67, 0xffff0000, v38
	v_lshlrev_b32_e32 v38, 16, v39
	s_waitcnt lgkmcnt(1)
	v_add_f32_e32 v0, v0, v65
	ds_bpermute_b32 v65, v156, v0
	s_waitcnt lgkmcnt(1)
	v_add_f32_e32 v64, v64, v80
	ds_bpermute_b32 v82, v156, v64
	v_and_b32_e32 v39, 0xffff0000, v39
	v_lshlrev_b32_e32 v80, 16, v68
	s_waitcnt lgkmcnt(1)
	v_add_f32_e32 v0, v0, v65
	ds_bpermute_b32 v65, v157, v0
	s_waitcnt lgkmcnt(1)
	v_add_f32_e32 v64, v64, v82
	ds_bpermute_b32 v84, v157, v64
	v_lshlrev_b32_e32 v68, 16, v69
	v_and_b32_e32 v69, 0xffff0000, v69
	s_waitcnt lgkmcnt(1)
	v_add_f32_e32 v0, v0, v65
	v_mul_f32_e32 v0, 0x3fb8aa3b, v0
	s_waitcnt lgkmcnt(0)
	v_add_f32_e32 v64, v64, v84
	v_mul_f32_e32 v64, 0x3fb8aa3b, v64
	v_exp_f32_e32 v0, v0
	v_exp_f32_e32 v64, v64
	v_lshlrev_b32_e32 v82, 16, v70
	v_and_b32_e32 v83, 0xffff0000, v70
	v_lshlrev_b32_e32 v70, 16, v71
	v_sub_f32_e32 v0, v0, v64
	v_add_f32_e32 v0, v165, v0
	v_pk_fma_f32 v[64:65], v[62:63], v[0:1], v[38:39] op_sel_hi:[1,0,1] neg_lo:[1,0,0] neg_hi:[1,0,0]
	v_pk_fma_f32 v[66:67], v[60:61], v[0:1], v[66:67] op_sel_hi:[1,0,1] neg_lo:[1,0,0] neg_hi:[1,0,0]
	v_pk_fma_f32 v[60:61], v[76:77], v[0:1], v[68:69] op_sel_hi:[1,0,1] neg_lo:[1,0,0] neg_hi:[1,0,0]
	v_pk_fma_f32 v[62:63], v[74:75], v[0:1], v[80:81] op_sel_hi:[1,0,1] neg_lo:[1,0,0] neg_hi:[1,0,0]
	v_and_b32_e32 v71, 0xffff0000, v71
	v_pk_fma_f32 v[68:69], v[48:49], v[0:1], v[82:83] op_sel_hi:[1,0,1] neg_lo:[1,0,0] neg_hi:[1,0,0]
	v_mov_b32_e32 v48, v67
	v_mov_b32_e32 v49, v63
	v_mov_b32_e32 v74, v65
	v_mov_b32_e32 v75, v61
	v_pk_fma_f32 v[70:71], v[50:51], v[0:1], v[70:71] op_sel_hi:[1,0,1] neg_lo:[1,0,0] neg_hi:[1,0,0]
	v_mov_b32_e32 v38, v66
	v_mov_b32_e32 v39, v62
	v_mov_b32_e32 v50, v64
	v_mov_b32_e32 v51, v60
	v_pk_mul_f32 v[48:49], v[48:49], v[48:49]
	v_pk_mul_f32 v[74:75], v[74:75], v[74:75]
	v_pk_fma_f32 v[38:39], v[38:39], v[38:39], v[48:49]
	v_pk_fma_f32 v[48:49], v[50:51], v[50:51], v[74:75]
	v_lshlrev_b32_e32 v84, 16, v72
	v_pk_mul_f32 v[76:77], v[70:71], v[70:71]
	v_pk_mul_f32 v[80:81], v[68:69], v[68:69]
	v_pk_add_f32 v[110:111], v[38:39], v[48:49]
	v_and_b32_e32 v85, 0xffff0000, v72
	v_lshlrev_b32_e32 v38, 16, v73
	v_and_b32_e32 v39, 0xffff0000, v73
	v_pk_mov_b32 v[82:83], v[80:81], v[76:77] op_sel:[1,0]
	v_mov_b32_e32 v81, v77
	v_pk_fma_f32 v[74:75], v[36:37], v[0:1], v[38:39] op_sel_hi:[1,0,1] neg_lo:[1,0,0] neg_hi:[1,0,0]
	v_pk_fma_f32 v[76:77], v[34:35], v[0:1], v[84:85] op_sel_hi:[1,0,1] neg_lo:[1,0,0] neg_hi:[1,0,0]
	v_lshlrev_b32_e32 v36, 16, v78
	v_and_b32_e32 v37, 0xffff0000, v78
	v_lshlrev_b32_e32 v34, 16, v79
	v_and_b32_e32 v35, 0xffff0000, v79
	v_pk_mul_f32 v[38:39], v[44:45], v[108:109] op_sel_hi:[1,0]
	v_pk_mul_f32 v[44:45], v[46:47], v[108:109] op_sel_hi:[1,0]
	v_pk_add_f32 v[104:105], v[82:83], v[80:81]
	v_pk_fma_f32 v[34:35], v[44:45], v[0:1], v[34:35] op_sel_hi:[1,0,1] neg_lo:[1,0,0] neg_hi:[1,0,0]
	v_pk_fma_f32 v[72:73], v[38:39], v[0:1], v[36:37] op_sel_hi:[1,0,1] neg_lo:[1,0,0] neg_hi:[1,0,0]
	global_load_dwordx4 v[96:99], v109, s[54:55]
	global_load_dwordx4 v[92:95], v109, s[54:55] offset:64
	global_load_dwordx4 v[88:91], v109, s[54:55] offset:128
	global_load_dwordx4 v[84:87], v109, s[54:55] offset:192
	global_load_dwordx4 v[80:83], v109, s[54:55] offset:256
	global_load_dwordx4 v[48:51], v109, s[54:55] offset:320
	global_load_dwordx4 v[44:47], v109, s[54:55] offset:384
	global_load_dwordx4 v[36:39], v109, s[54:55] offset:448
	s_waitcnt vmcnt(15)
	v_mov_b32_e32 v112, v186
	v_mov_b32_e32 v113, v187
	v_pk_add_f32 v[78:79], v[110:111], v[110:111] op_sel:[0,1] op_sel_hi:[1,0]
	s_waitcnt vmcnt(14)
	v_mov_b32_e32 v110, v188
	v_mov_b32_e32 v111, v189
	v_mul_f32_e32 v114, v72, v72
	v_mul_f32_e32 v115, v73, v73
	v_pk_add_f32 v[104:105], v[104:105], v[104:105] op_sel:[0,1] op_sel_hi:[1,0]
	v_mov_b32_e32 v79, v114
	v_mov_b32_e32 v105, v115
	v_pk_add_f32 v[78:79], v[78:79], v[104:105]
	v_mul_f32_e32 v104, v77, v77
	v_mul_f32_e32 v114, v75, v75
	v_mul_f32_e32 v116, v34, v34
	v_mul_f32_e32 v109, v35, v35
	v_pk_fma_f32 v[104:105], v[76:77], v[76:77], v[104:105] op_sel_hi:[1,1,0]
	v_pk_fma_f32 v[114:115], v[74:75], v[74:75], v[114:115] op_sel_hi:[1,1,0]
	v_mov_b32_e32 v105, v116
	v_mov_b32_e32 v115, v109
	v_pk_add_f32 v[104:105], v[104:105], v[114:115]
	v_pk_mul_f32 v[58:59], v[58:59], v[108:109] op_sel_hi:[1,0]
	v_pk_add_f32 v[114:115], v[78:79], v[104:105]
	v_lshlrev_b32_e32 v78, 16, v100
	v_and_b32_e32 v79, 0xffff0000, v100
	v_lshlrev_b32_e32 v100, 16, v101
	v_and_b32_e32 v101, 0xffff0000, v101
	v_pk_mul_f32 v[56:57], v[56:57], v[108:109] op_sel_hi:[1,0]
	v_pk_fma_f32 v[100:101], v[58:59], v[0:1], v[100:101] op_sel_hi:[1,0,1] neg_lo:[1,0,0] neg_hi:[1,0,0]
	v_pk_fma_f32 v[78:79], v[56:57], v[0:1], v[78:79] op_sel_hi:[1,0,1] neg_lo:[1,0,0] neg_hi:[1,0,0]
	v_pk_mul_f32 v[56:57], v[100:101], v[100:101]
	v_pk_mul_f32 v[58:59], v[78:79], v[78:79]
	v_pk_mul_f32 v[52:53], v[52:53], v[108:109] op_sel_hi:[1,0]
	v_pk_mov_b32 v[104:105], v[58:59], v[56:57] op_sel:[1,0]
	v_mov_b32_e32 v59, v57
	v_pk_add_f32 v[56:57], v[104:105], v[58:59]
	v_lshlrev_b32_e32 v58, 16, v102
	v_and_b32_e32 v59, 0xffff0000, v102
	v_pk_fma_f32 v[104:105], v[52:53], v[0:1], v[58:59] op_sel_hi:[1,0,1] neg_lo:[1,0,0] neg_hi:[1,0,0]
	v_lshlrev_b32_e32 v52, 16, v106
	v_and_b32_e32 v53, 0xffff0000, v106
	v_pk_mul_f32 v[40:41], v[40:41], v[108:109] op_sel_hi:[1,0]
	s_waitcnt vmcnt(13)
	v_mov_b32_e32 v116, v190
	v_mov_b32_e32 v117, v191
	v_lshlrev_b32_e32 v102, 16, v103
	v_and_b32_e32 v103, 0xffff0000, v103
	v_pk_mul_f32 v[54:55], v[54:55], v[108:109] op_sel_hi:[1,0]
	v_pk_mul_f32 v[42:43], v[42:43], v[108:109] op_sel_hi:[1,0]
	v_pk_fma_f32 v[108:109], v[40:41], v[0:1], v[52:53] op_sel_hi:[1,0,1] neg_lo:[1,0,0] neg_hi:[1,0,0]
	v_pk_fma_f32 v[102:103], v[54:55], v[0:1], v[102:103] op_sel_hi:[1,0,1] neg_lo:[1,0,0] neg_hi:[1,0,0]
	v_lshlrev_b32_e32 v54, 16, v107
	v_and_b32_e32 v55, 0xffff0000, v107
	v_mul_f32_e32 v52, v108, v108
	v_pk_add_f32 v[40:41], v[114:115], v[114:115] op_sel:[0,1] op_sel_hi:[1,0]
	v_pk_fma_f32 v[106:107], v[42:43], v[0:1], v[54:55] op_sel_hi:[1,0,1] neg_lo:[1,0,0] neg_hi:[1,0,0]
	v_mul_f32_e32 v54, v109, v109
	v_mov_b32_e32 v41, v52
	v_pk_add_f32 v[52:53], v[56:57], v[56:57] op_sel:[0,1] op_sel_hi:[1,0]
	s_waitcnt vmcnt(12)
	v_mov_b32_e32 v58, v192
	v_mov_b32_e32 v59, v193
	v_mov_b32_e32 v53, v54
	v_pk_add_f32 v[40:41], v[40:41], v[52:53]
	v_mul_f32_e32 v52, v105, v105
	v_div_scale_f32 v56, s[6:7], v118, v118, 1.0
	v_mul_f32_e32 v55, v106, v106
	s_waitcnt vmcnt(11)
	v_mov_b32_e32 v42, v194
	v_mov_b32_e32 v43, v195
	v_pk_fma_f32 v[52:53], v[104:105], v[104:105], v[52:53] op_sel_hi:[1,1,0]
	v_mul_f32_e32 v54, v103, v103
	v_rcp_f32_e32 v57, v56
	v_mul_f32_e32 v119, v107, v107
	v_mov_b32_e32 v53, v55
	v_pk_fma_f32 v[54:55], v[102:103], v[102:103], v[54:55] op_sel_hi:[1,1,0]
	s_brev_b32 s6, 60
	v_mov_b32_e32 v55, v119
	v_pk_add_f32 v[52:53], v[52:53], v[54:55]
	s_nop 0
	v_pk_add_f32 v[40:41], v[40:41], v[52:53]
	v_fma_f32 v52, -v56, v57, 1.0
	v_fmac_f32_e32 v57, v52, v57
	v_div_scale_f32 v52, vcc, 1.0, v118, 1.0
	v_mul_f32_e32 v54, v52, v57
	v_fma_f32 v53, -v56, v54, v52
	v_fmac_f32_e32 v54, v53, v57
	v_fma_f32 v55, -v56, v54, v52
	s_waitcnt vmcnt(10)
	v_mov_b32_e32 v52, v196
	v_mov_b32_e32 v53, v197
	v_div_fmas_f32 v54, v55, v57, v54
	v_div_fixup_f32 v54, v54, v118, 1.0
	s_waitcnt lgkmcnt(0)
	v_lshlrev_b32_e32 v56, 16, v112
	v_and_b32_e32 v57, 0xffff0000, v112
	v_lshlrev_b32_e32 v112, 16, v113
	v_and_b32_e32 v113, 0xffff0000, v113
	v_pk_mul_f32 v[114:115], v[30:31], v[54:55] op_sel_hi:[1,0]
	v_pk_mul_f32 v[30:31], v[32:33], v[54:55] op_sel_hi:[1,0]
	v_pk_fma_f32 v[32:33], v[114:115], v[0:1], v[56:57] op_sel_hi:[1,0,1] neg_lo:[1,0,0] neg_hi:[1,0,0]
	v_pk_fma_f32 v[30:31], v[30:31], v[0:1], v[112:113] op_sel_hi:[1,0,1] neg_lo:[1,0,0] neg_hi:[1,0,0]
	v_lshlrev_b32_e32 v56, 16, v110
	v_and_b32_e32 v57, 0xffff0000, v110
	s_waitcnt vmcnt(9)
	v_mov_b32_e32 v112, v198
	v_mov_b32_e32 v113, v199
	v_lshlrev_b32_e32 v110, 16, v111
	v_and_b32_e32 v111, 0xffff0000, v111
	v_pk_mul_f32 v[26:27], v[26:27], v[54:55] op_sel_hi:[1,0]
	v_pk_mul_f32 v[28:29], v[28:29], v[54:55] op_sel_hi:[1,0]
	v_mov_b32_e32 v114, v33
	v_pk_fma_f32 v[28:29], v[28:29], v[0:1], v[110:111] op_sel_hi:[1,0,1] neg_lo:[1,0,0] neg_hi:[1,0,0]
	v_pk_fma_f32 v[110:111], v[26:27], v[0:1], v[56:57] op_sel_hi:[1,0,1] neg_lo:[1,0,0] neg_hi:[1,0,0]
	s_waitcnt vmcnt(0)
	v_mov_b32_e32 v56, v200
	v_mov_b32_e32 v57, v201
	v_mov_b32_e32 v115, v111
	v_mov_b32_e32 v26, v32
	v_mov_b32_e32 v27, v110
	v_pk_mul_f32 v[114:115], v[114:115], v[114:115]
	v_mov_b32_e32 v118, v31
	v_mov_b32_e32 v119, v29
	v_pk_fma_f32 v[26:27], v[26:27], v[26:27], v[114:115]
	v_mov_b32_e32 v114, v30
	v_mov_b32_e32 v115, v28
	v_pk_mul_f32 v[118:119], v[118:119], v[118:119]
	v_pk_mul_f32 v[20:21], v[20:21], v[54:55] op_sel_hi:[1,0]
	v_pk_fma_f32 v[114:115], v[114:115], v[114:115], v[118:119]
	v_pk_mul_f32 v[18:19], v[18:19], v[54:55] op_sel_hi:[1,0]
	v_pk_add_f32 v[26:27], v[26:27], v[114:115]
	v_pk_mul_f32 v[16:17], v[16:17], v[54:55] op_sel_hi:[1,0]
	v_pk_mul_f32 v[22:23], v[22:23], v[54:55] op_sel_hi:[1,0]
	v_lshlrev_b32_e32 v114, 16, v116
	v_and_b32_e32 v115, 0xffff0000, v116
	v_lshlrev_b32_e32 v116, 16, v117
	v_and_b32_e32 v117, 0xffff0000, v117
	v_pk_fma_f32 v[18:19], v[18:19], v[0:1], v[114:115] op_sel_hi:[1,0,1] neg_lo:[1,0,0] neg_hi:[1,0,0]
	v_pk_fma_f32 v[20:21], v[20:21], v[0:1], v[116:117] op_sel_hi:[1,0,1] neg_lo:[1,0,0] neg_hi:[1,0,0]
	v_pk_mul_f32 v[116:117], v[18:19], v[18:19]
	v_pk_mul_f32 v[114:115], v[20:21], v[20:21]
	v_pk_mul_f32 v[14:15], v[14:15], v[54:55] op_sel_hi:[1,0]
	v_pk_mov_b32 v[118:119], v[116:117], v[114:115] op_sel:[1,0]
	v_mov_b32_e32 v117, v115
	v_pk_add_f32 v[114:115], v[118:119], v[116:117]
	v_pk_mul_f32 v[24:25], v[24:25], v[54:55] op_sel_hi:[1,0]
	v_lshlrev_b32_e32 v116, 16, v58
	v_and_b32_e32 v117, 0xffff0000, v58
	v_lshlrev_b32_e32 v58, 16, v59
	v_and_b32_e32 v59, 0xffff0000, v59
	v_pk_fma_f32 v[16:17], v[16:17], v[0:1], v[58:59] op_sel_hi:[1,0,1] neg_lo:[1,0,0] neg_hi:[1,0,0]
	v_pk_fma_f32 v[14:15], v[14:15], v[0:1], v[116:117] op_sel_hi:[1,0,1] neg_lo:[1,0,0] neg_hi:[1,0,0]
	v_lshlrev_b32_e32 v58, 16, v42
	v_and_b32_e32 v59, 0xffff0000, v42
	v_lshlrev_b32_e32 v42, 16, v43
	v_and_b32_e32 v43, 0xffff0000, v43
	v_pk_fma_f32 v[118:119], v[22:23], v[0:1], v[58:59] op_sel_hi:[1,0,1] neg_lo:[1,0,0] neg_hi:[1,0,0]
	v_pk_fma_f32 v[116:117], v[24:25], v[0:1], v[42:43] op_sel_hi:[1,0,1] neg_lo:[1,0,0] neg_hi:[1,0,0]
	v_mul_f32_e32 v24, v118, v118
	v_pk_add_f32 v[22:23], v[26:27], v[26:27] op_sel:[0,1] op_sel_hi:[1,0]
	v_mul_f32_e32 v42, v119, v119
	v_mov_b32_e32 v23, v24
	v_pk_add_f32 v[24:25], v[114:115], v[114:115] op_sel:[0,1] op_sel_hi:[1,0]
	v_mul_f32_e32 v26, v17, v17
	v_mov_b32_e32 v25, v42
	v_pk_add_f32 v[22:23], v[22:23], v[24:25]
	v_mul_f32_e32 v24, v15, v15
	v_mul_f32_e32 v43, v116, v116
	v_mul_f32_e32 v55, v117, v117
	v_pk_fma_f32 v[24:25], v[14:15], v[14:15], v[24:25] op_sel_hi:[1,1,0]
	v_pk_fma_f32 v[26:27], v[16:17], v[16:17], v[26:27] op_sel_hi:[1,1,0]
	v_mov_b32_e32 v25, v43
	v_mov_b32_e32 v27, v55
	v_pk_add_f32 v[24:25], v[24:25], v[26:27]
	v_lshlrev_b32_e32 v26, 16, v53
	v_pk_add_f32 v[22:23], v[22:23], v[24:25]
	v_lshlrev_b32_e32 v24, 16, v52
	v_and_b32_e32 v25, 0xffff0000, v52
	v_and_b32_e32 v27, 0xffff0000, v53
	v_pk_mul_f32 v[12:13], v[12:13], v[54:55] op_sel_hi:[1,0]
	v_pk_mul_f32 v[10:11], v[10:11], v[54:55] op_sel_hi:[1,0]
	v_pk_fma_f32 v[12:13], v[12:13], v[0:1], v[26:27] op_sel_hi:[1,0,1] neg_lo:[1,0,0] neg_hi:[1,0,0]
	v_pk_fma_f32 v[10:11], v[10:11], v[0:1], v[24:25] op_sel_hi:[1,0,1] neg_lo:[1,0,0] neg_hi:[1,0,0]
	v_pk_mul_f32 v[24:25], v[12:13], v[12:13]
	v_pk_mul_f32 v[26:27], v[10:11], v[10:11]
	v_pk_mul_f32 v[6:7], v[6:7], v[54:55] op_sel_hi:[1,0]
	v_pk_mov_b32 v[42:43], v[26:27], v[24:25] op_sel:[1,0]
	v_mov_b32_e32 v27, v25
	v_pk_add_f32 v[24:25], v[42:43], v[26:27]
	s_waitcnt lgkmcnt(0)
	v_lshlrev_b32_e32 v26, 16, v112
	v_and_b32_e32 v27, 0xffff0000, v112
	v_lshlrev_b32_e32 v42, 16, v113
	v_and_b32_e32 v43, 0xffff0000, v113
	v_pk_mul_f32 v[8:9], v[8:9], v[54:55] op_sel_hi:[1,0]
	v_pk_fma_f32 v[6:7], v[6:7], v[0:1], v[26:27] op_sel_hi:[1,0,1] neg_lo:[1,0,0] neg_hi:[1,0,0]
	v_lshlrev_b32_e32 v26, 16, v56
	v_and_b32_e32 v27, 0xffff0000, v56
	v_pk_mul_f32 v[2:3], v[2:3], v[54:55] op_sel_hi:[1,0]
	v_pk_fma_f32 v[8:9], v[8:9], v[0:1], v[42:43] op_sel_hi:[1,0,1] neg_lo:[1,0,0] neg_hi:[1,0,0]
	v_lshlrev_b32_e32 v42, 16, v57
	v_and_b32_e32 v43, 0xffff0000, v57
	v_pk_mul_f32 v[4:5], v[4:5], v[54:55] op_sel_hi:[1,0]
	v_pk_fma_f32 v[2:3], v[2:3], v[0:1], v[26:27] op_sel_hi:[1,0,1] neg_lo:[1,0,0] neg_hi:[1,0,0]
	v_pk_fma_f32 v[4:5], v[4:5], v[0:1], v[42:43] op_sel_hi:[1,0,1] neg_lo:[1,0,0] neg_hi:[1,0,0]
	v_mul_f32_e32 v0, v2, v2
	v_mul_f32_e32 v26, v3, v3
	v_pk_add_f32 v[22:23], v[22:23], v[22:23] op_sel:[0,1] op_sel_hi:[1,0]
	v_pk_add_f32 v[24:25], v[24:25], v[24:25] op_sel:[0,1] op_sel_hi:[1,0]
	v_mov_b32_e32 v23, v0
	v_mov_b32_e32 v25, v26
	v_mul_f32_e32 v0, v7, v7
	v_mul_f32_e32 v27, v4, v4
	v_pk_add_f32 v[22:23], v[22:23], v[24:25]
	v_pk_fma_f32 v[24:25], v[6:7], v[6:7], v[0:1] op_sel_hi:[1,1,0]
	v_mul_f32_e32 v0, v9, v9
	v_mul_f32_e32 v42, v5, v5
	v_mov_b32_e32 v25, v27
	v_pk_fma_f32 v[26:27], v[8:9], v[8:9], v[0:1] op_sel_hi:[1,1,0]
	s_nop 0
	v_mov_b32_e32 v27, v42
	v_pk_add_f32 v[24:25], v[24:25], v[26:27]
	s_nop 0
	v_pk_add_f32 v[22:23], v[22:23], v[24:25]
	v_mov_b32_e32 v25, v40
	v_mov_b32_e32 v24, v22
	v_mov_b32_e32 v40, v23
	v_pk_add_f32 v[22:23], v[24:25], v[40:41]
	ds_bpermute_b32 v25, v156, v23
	ds_bpermute_b32 v24, v156, v22
	s_waitcnt lgkmcnt(0)
	v_pk_add_f32 v[22:23], v[22:23], v[24:25]
	ds_bpermute_b32 v25, v157, v23
	ds_bpermute_b32 v24, v157, v22
	s_waitcnt lgkmcnt(0)
	v_pk_add_f32 v[22:23], v[22:23], v[24:25]
	s_nop 0
	v_pk_fma_f32 v[22:23], v[22:23], s[6:7], v[162:163] op_sel_hi:[1,0,0]
	s_nop 0
	v_mul_f32_e32 v0, 0x4b800000, v23
	v_cmp_gt_f32_e32 vcc, s80, v23
	s_nop 1
	v_cndmask_b32_e32 v0, v23, v0, vcc
	v_rsq_f32_e32 v0, v0
	s_nop 0
	v_mul_f32_e32 v23, 0x45800000, v0
	v_cndmask_b32_e32 v0, v0, v23, vcc
	v_mul_f32_e32 v0, v166, v0
	v_pk_mul_f32 v[26:27], v[64:65], v[0:1] op_sel_hi:[1,0]
	v_pk_mul_f32 v[24:25], v[66:67], v[0:1] op_sel_hi:[1,0]
	v_pk_mul_f32 v[66:67], v[98:99], v[26:27]
	v_pk_mul_f32 v[26:27], v[60:61], v[0:1] op_sel_hi:[1,0]
	v_pk_mul_f32 v[64:65], v[96:97], v[24:25]
	v_pk_mul_f32 v[24:25], v[62:63], v[0:1] op_sel_hi:[1,0]
	v_pk_mul_f32 v[62:63], v[94:95], v[26:27]
	v_pk_mul_f32 v[26:27], v[70:71], v[0:1] op_sel_hi:[1,0]
	v_mul_f32_e32 v23, 0x4b800000, v22
	v_pk_mul_f32 v[58:59], v[90:91], v[26:27]
	v_pk_mul_f32 v[26:27], v[74:75], v[0:1] op_sel_hi:[1,0]
	v_cmp_gt_f32_e32 vcc, s80, v22
	v_pk_mul_f32 v[54:55], v[86:87], v[26:27]
	v_pk_mul_f32 v[26:27], v[34:35], v[0:1] op_sel_hi:[1,0]
	v_pk_mul_f32 v[60:61], v[92:93], v[24:25]
	v_pk_mul_f32 v[42:43], v[82:83], v[26:27]
	v_pk_mul_f32 v[26:27], v[100:101], v[0:1] op_sel_hi:[1,0]
	v_pk_mul_f32 v[24:25], v[68:69], v[0:1] op_sel_hi:[1,0]
	v_pk_mul_f32 v[70:71], v[50:51], v[26:27]
	v_pk_mul_f32 v[26:27], v[102:103], v[0:1] op_sel_hi:[1,0]
	v_cndmask_b32_e32 v22, v22, v23, vcc
	v_pk_mul_f32 v[56:57], v[88:89], v[24:25]
	v_pk_mul_f32 v[24:25], v[76:77], v[0:1] op_sel_hi:[1,0]
	v_pk_mul_f32 v[74:75], v[46:47], v[26:27]
	v_rsq_f32_e32 v26, v22
	v_pk_mul_f32 v[52:53], v[84:85], v[24:25]
	v_pk_mul_f32 v[24:25], v[72:73], v[0:1] op_sel_hi:[1,0]
	v_pk_mul_f32 v[22:23], v[106:107], v[0:1] op_sel_hi:[1,0]
	v_pk_mul_f32 v[40:41], v[80:81], v[24:25]
	v_pk_mul_f32 v[24:25], v[78:79], v[0:1] op_sel_hi:[1,0]
	v_pk_mul_f32 v[78:79], v[38:39], v[22:23]
	v_pk_mul_f32 v[68:69], v[48:49], v[24:25]
	v_pk_mul_f32 v[24:25], v[104:105], v[0:1] op_sel_hi:[1,0]
	s_nop 0
	v_pk_mul_f32 v[72:73], v[44:45], v[24:25]
	v_pk_mul_f32 v[24:25], v[108:109], v[0:1] op_sel_hi:[1,0]
	v_mul_f32_e32 v0, 0x45800000, v26
	v_cndmask_b32_e32 v0, v26, v0, vcc
	v_mul_f32_e32 v0, v166, v0
	v_pk_mul_f32 v[76:77], v[36:37], v[24:25]
	v_pk_mul_f32 v[22:23], v[32:33], v[0:1] op_sel_hi:[1,0]
	v_pk_mul_f32 v[24:25], v[30:31], v[0:1] op_sel_hi:[1,0]
	v_pk_mul_f32 v[28:29], v[28:29], v[0:1] op_sel_hi:[1,0]
	v_pk_mul_f32 v[26:27], v[98:99], v[24:25]
	v_pk_mul_f32 v[24:25], v[96:97], v[22:23]
	v_pk_mul_f32 v[22:23], v[110:111], v[0:1] op_sel_hi:[1,0]
	v_pk_mul_f32 v[20:21], v[20:21], v[0:1] op_sel_hi:[1,0]
	v_pk_mul_f32 v[14:15], v[14:15], v[0:1] op_sel_hi:[1,0]
	v_pk_mul_f32 v[16:17], v[16:17], v[0:1] op_sel_hi:[1,0]
	v_pk_mul_f32 v[30:31], v[94:95], v[28:29]
	v_pk_mul_f32 v[28:29], v[92:93], v[22:23]
	v_pk_mul_f32 v[18:19], v[18:19], v[0:1] op_sel_hi:[1,0]
	v_pk_mul_f32 v[34:35], v[90:91], v[20:21]
	v_pk_mul_f32 v[22:23], v[86:87], v[16:17]
	v_pk_mul_f32 v[20:21], v[84:85], v[14:15]
	v_pk_mul_f32 v[14:15], v[118:119], v[0:1] op_sel_hi:[1,0]
	v_pk_mul_f32 v[16:17], v[116:117], v[0:1] op_sel_hi:[1,0]
	v_pk_mul_f32 v[10:11], v[10:11], v[0:1] op_sel_hi:[1,0]
	v_pk_mul_f32 v[12:13], v[12:13], v[0:1] op_sel_hi:[1,0]
	v_pk_mul_f32 v[6:7], v[6:7], v[0:1] op_sel_hi:[1,0]
	v_pk_mul_f32 v[8:9], v[8:9], v[0:1] op_sel_hi:[1,0]
	v_pk_mul_f32 v[2:3], v[2:3], v[0:1] op_sel_hi:[1,0]
	v_pk_mul_f32 v[4:5], v[4:5], v[0:1] op_sel_hi:[1,0]
	v_pk_mul_f32 v[32:33], v[88:89], v[18:19]
	v_pk_mul_f32 v[18:19], v[82:83], v[16:17]
	v_pk_mul_f32 v[16:17], v[80:81], v[14:15]
	v_pk_mul_f32 v[14:15], v[50:51], v[12:13]
	v_pk_mul_f32 v[12:13], v[48:49], v[10:11]
	v_pk_mul_f32 v[10:11], v[46:47], v[8:9]
	v_pk_mul_f32 v[8:9], v[44:45], v[6:7]
	v_pk_mul_f32 v[6:7], v[38:39], v[4:5]
	v_pk_mul_f32 v[4:5], v[36:37], v[2:3]
	v_mov_b32_e32 v3, 1.0
	v_mov_b32_e32 v2, v3
	s_mov_b64 s[6:7], s[28:29]
	s_mov_b64 s[72:73], 0x26000
